# final RMSNorm loop: gain loads hoisted out of the loop and row loads software-pipelined one row ahead; on top of v76
# baseline (speedup 1.0000x reference)
.LBB0_72:
	s_cmp_eq_u32 s56, 27
	s_mov_b64 s[2:3], -1
	s_cbranch_scc0 .LBB0_77
	s_waitcnt lgkmcnt(0)
	v_mov_b32_e32 v4, v180
	v_mov_b32_e32 v0, v180
	v_readlane_b32 s2, v254, 14
	v_readlane_b32 s3, v254, 15
	s_nop 0
	v_add_u32_e32 v0, s2, v0
	s_mov_b32 s2, 0x200000
	v_cmp_gt_u32_e32 vcc, s2, v0
	s_and_saveexec_b64 s[2:3], vcc
	v_readlane_b32 s52, v254, 4
	v_readlane_b32 s31, v254, 37
	v_readlane_b32 s53, v254, 5
	s_mov_b32 s54, 0x800000
	s_movk_i32 s55, 0x7fff
	s_cbranch_execz .LBB0_76
	v_cmp_lt_i32_e32 vcc, v248, v187
	v_lshrrev_b32_e32 v8, 6, v0
	v_readlane_b32 s36, v251, 63
	v_cndmask_b32_e32 v0, v186, v248, vcc
	v_cmp_lt_i32_e32 vcc, v181, v187
	v_lshlrev_b32_e32 v9, 2, v0
	v_readlane_b32 s48, v252, 11
	v_cndmask_b32_e32 v0, v186, v181, vcc
	v_cmp_lt_i32_e32 vcc, v190, v187
	v_lshlrev_b32_e32 v10, 2, v0
	v_readlane_b32 s49, v252, 12
	v_cndmask_b32_e32 v0, v186, v190, vcc
	v_cmp_lt_i32_e32 vcc, v191, v187
	v_lshlrev_b32_e32 v11, 2, v0
	v_and_b32_e32 v15, 63, v4
	v_cndmask_b32_e32 v0, v186, v191, vcc
	v_cmp_lt_i32_e32 vcc, v192, v187
	v_lshlrev_b32_e32 v12, 2, v0
	v_readlane_b32 s28, v253, 40
	v_cndmask_b32_e32 v0, v186, v192, vcc
	v_cmp_lt_i32_e32 vcc, v193, v187
	v_lshlrev_b32_e32 v13, 2, v0
	v_readlane_b32 s29, v253, 41
	v_cndmask_b32_e32 v0, v186, v193, vcc
	v_lshlrev_b32_e32 v14, 2, v0
	v_lshlrev_b32_e32 v0, 5, v4
	v_and_b32_e32 v0, 0x7e0, v0
	v_lshl_add_u64 v[2:3], s[48:49], 0, v[0:1]
	v_lshlrev_b32_e32 v0, 10, v8
	v_lshlrev_b64 v[6:7], 1, v[0:1]
	v_lshl_or_b32 v6, v15, 4, v6
	v_lshl_add_u64 v[4:5], s[28:29], 0, v[6:7]
	v_lshlrev_b64 v[6:7], 2, v[0:1]
	v_lshl_or_b32 v6, v15, 5, v6
	v_lshl_add_u64 v[6:7], s[24:25], 0, v[6:7]
	s_mov_b64 s[28:29], 0
	v_readlane_b32 s37, v252, 0
	v_readlane_b32 s38, v252, 1
	v_readlane_b32 s39, v252, 2
	v_readlane_b32 s40, v252, 3
	v_readlane_b32 s41, v252, 4
	v_readlane_b32 s42, v252, 5
	v_readlane_b32 s43, v252, 6
	v_readlane_b32 s44, v252, 7
	v_readlane_b32 s45, v252, 8
	v_readlane_b32 s46, v252, 9
	v_readlane_b32 s47, v252, 10
	v_readlane_b32 s50, v252, 13
	v_readlane_b32 s51, v252, 14
	global_load_dwordx4 v[64:67], v[2:3], off offset:16
	global_load_dwordx4 v[68:71], v[2:3], off
	global_load_dwordx4 v[72:75], v[2:3], off offset:2048
	global_load_dwordx4 v[76:79], v[2:3], off offset:2064
	global_load_dwordx4 v[56:59], v[4:5], off
	global_load_dwordx4 v[60:63], v[4:5], off offset:1024
	v_lshl_add_u64 v[4:5], v[4:5], 0, s[72:73]
	s_waitcnt vmcnt(0)
.LBB0_75:
	s_waitcnt vmcnt(4)
	v_mov_b32_e32 v16, v56
	v_mov_b32_e32 v17, v57
	v_mov_b32_e32 v18, v58
	v_mov_b32_e32 v19, v59
	v_mov_b32_e32 v20, v60
	v_mov_b32_e32 v21, v61
	v_mov_b32_e32 v22, v62
	v_mov_b32_e32 v23, v63
	global_load_dwordx4 v[56:59], v[4:5], off
	global_load_dwordx4 v[60:63], v[4:5], off offset:1024
	v_add_u32_e32 v8, s31, v8
	v_lshl_add_u64 v[4:5], v[4:5], 0, s[72:73]
	v_lshlrev_b32_e32 v32, 16, v16
	v_and_b32_e32 v33, 0xffff0000, v16
	v_lshlrev_b32_e32 v16, 16, v17
	v_and_b32_e32 v17, 0xffff0000, v17
	v_lshlrev_b32_e32 v36, 16, v20
	v_and_b32_e32 v37, 0xffff0000, v20
	v_lshlrev_b32_e32 v38, 16, v21
	v_and_b32_e32 v39, 0xffff0000, v21
	v_pk_mul_f32 v[20:21], v[32:33], v[32:33]
	v_lshlrev_b32_e32 v40, 16, v22
	v_and_b32_e32 v41, 0xffff0000, v22
	v_lshlrev_b32_e32 v42, 16, v23
	v_and_b32_e32 v43, 0xffff0000, v23
	v_pk_mul_f32 v[22:23], v[16:17], v[16:17]
	v_add_f32_e32 v0, v20, v21
	v_lshlrev_b32_e32 v34, 16, v18
	v_and_b32_e32 v35, 0xffff0000, v18
	v_add_f32_e32 v0, v22, v0
	v_pk_mul_f32 v[44:45], v[34:35], v[34:35]
	v_add_f32_e32 v0, v23, v0
	v_lshlrev_b32_e32 v18, 16, v19
	v_and_b32_e32 v19, 0xffff0000, v19
	v_add_f32_e32 v0, v44, v0
	v_pk_mul_f32 v[46:47], v[18:19], v[18:19]
	v_add_f32_e32 v0, v45, v0
	v_add_f32_e32 v0, v46, v0
	v_pk_mul_f32 v[48:49], v[36:37], v[36:37]
	v_add_f32_e32 v0, v47, v0
	v_add_f32_e32 v0, v48, v0
	v_pk_mul_f32 v[50:51], v[38:39], v[38:39]
	v_add_f32_e32 v0, v49, v0
	v_add_f32_e32 v0, v50, v0
	v_pk_mul_f32 v[52:53], v[40:41], v[40:41]
	v_add_f32_e32 v0, v51, v0
	v_add_f32_e32 v0, v52, v0
	v_pk_mul_f32 v[54:55], v[42:43], v[42:43]
	v_add_f32_e32 v0, v53, v0
	v_add_f32_e32 v0, v54, v0
	v_add_f32_e32 v0, v55, v0
	ds_bpermute_b32 v15, v9, v0
	s_waitcnt lgkmcnt(0)
	v_add_f32_e32 v0, v0, v15
	ds_bpermute_b32 v15, v10, v0
	s_waitcnt lgkmcnt(0)
	v_add_f32_e32 v0, v0, v15
	ds_bpermute_b32 v15, v11, v0
	s_waitcnt lgkmcnt(0)
	v_add_f32_e32 v0, v0, v15
	ds_bpermute_b32 v15, v12, v0
	s_waitcnt lgkmcnt(0)
	v_add_f32_e32 v0, v0, v15
	ds_bpermute_b32 v15, v13, v0
	s_waitcnt lgkmcnt(0)
	v_add_f32_e32 v0, v0, v15
	ds_bpermute_b32 v15, v14, v0
	s_waitcnt lgkmcnt(0)
	v_add_f32_e32 v0, v0, v15
	v_fmamk_f32 v0, v0, 0x3a800000, v184
	v_mul_f32_e32 v15, 0x4b800000, v0
	v_cmp_gt_f32_e32 vcc, s54, v0
	s_nop 1
	v_cndmask_b32_e32 v0, v0, v15, vcc
	v_rsq_f32_e32 v0, v0
	s_nop 0
	v_mul_f32_e32 v15, 0x45800000, v0
	v_cndmask_b32_e32 v0, v0, v15, vcc
	v_pk_mul_f32 v[20:21], v[0:1], v[32:33] op_sel_hi:[0,1]
	v_pk_mul_f32 v[16:17], v[0:1], v[16:17] op_sel_hi:[0,1]
	v_pk_mul_f32 v[32:33], v[0:1], v[34:35] op_sel_hi:[0,1]
	v_pk_mul_f32 v[22:23], v[0:1], v[18:19] op_sel_hi:[0,1]
	v_pk_mul_f32 v[18:19], v[70:71], v[16:17]
	v_pk_mul_f32 v[16:17], v[68:69], v[20:21]
	v_pk_mul_f32 v[22:23], v[66:67], v[22:23]
	v_pk_mul_f32 v[20:21], v[64:65], v[32:33]
	global_store_dwordx4 v[6:7], v[16:19], off
	global_store_dwordx4 v[6:7], v[20:23], off offset:16
	s_nop 0
	v_pk_mul_f32 v[24:25], v[0:1], v[38:39] op_sel_hi:[0,1]
	v_pk_mul_f32 v[26:27], v[0:1], v[36:37] op_sel_hi:[0,1]
	v_cmp_lt_u32_e32 vcc, s55, v8
	v_pk_mul_f32 v[28:29], v[0:1], v[42:43] op_sel_hi:[0,1]
	v_pk_mul_f32 v[30:31], v[0:1], v[40:41] op_sel_hi:[0,1]
	s_or_b64 s[28:29], vcc, s[28:29]
	v_pk_mul_f32 v[16:17], v[72:73], v[26:27]
	v_pk_mul_f32 v[18:19], v[74:75], v[24:25]
	v_pk_mul_f32 v[20:21], v[76:77], v[30:31]
	v_pk_mul_f32 v[22:23], v[78:79], v[28:29]
	global_store_dwordx4 v[6:7], v[16:19], off offset:2048
	global_store_dwordx4 v[6:7], v[20:23], off offset:2064
	v_lshl_add_u64 v[6:7], v[6:7], 0, s[52:53]
	s_andn2_b64 exec, exec, s[28:29]
	s_cbranch_execnz .LBB0_75
